# phase F first epilogue: each lane touches its seven other gate lines up front so the 16 dependent per-quad gate fetches hit L2
# speedup vs baseline: 1.0175x; 1.0053x over previous
; DI uint2 pk4(float a, float b, float c, float d) { uint2 o; o.x = pk2(a, b); o.y = pk2(c, d); return o; }
; DI float sigmoidf_(float x) { return 1.f / (1.f + __expf(-x)); }
; DI void phaseF(int wv0, PP p, unsigned char* smem) {
;     ...
;       for (int ai = 0; ai < 2; ++ai)
; #pragma unroll
;         for (int m = 0; m < 4; ++m)
; #pragma unroll
;           for (int n = 0; n < 2; ++n)
; #pragma unroll
;             for (int j = 0; j < 4; ++j) acc[ai][0][m][n][j] *= sigmoidf_(acc[ai][1][m][n][j]);
;       __builtin_amdgcn_sched_barrier(0);
;       epi256(wv0, acc, brow, grp * 128, [&](int ai, int bj, int m, int n, int row, int col0, f32x4& v) {
;         if (bj == 0) {
;           const unsigned og = (unsigned)row * 2048u + 1024u + (unsigned)col0, om = (unsigned)row * 1024u + (unsigned)col0;
;           const uint2 gq = *(const uint2*)(MG + og);
;           *(uint2*)(MR + om) = pk4(__uint_as_float(gq.x << 16) * v[0], __uint_as_float(gq.x & 0xffff0000u) * v[1],
;                                    __uint_as_float(gq.y << 16) * v[2], __uint_as_float(gq.y & 0xffff0000u) * v[3]);
;         }
;       });
.LBB0_982:
	v_mul_f32_e32 v116, 0xbfb8aa3b, v116
	v_exp_f32_e32 v140, v116
	v_mul_f32_e32 v116, 0xbfb8aa3b, v117
	v_mul_f32_e32 v76, 0xbfb8aa3b, v76
	v_exp_f32_e32 v141, v116
	v_mul_f32_e32 v116, 0xbfb8aa3b, v118
	v_exp_f32_e32 v118, v76
	v_mul_f32_e32 v76, 0xbfb8aa3b, v77
	v_exp_f32_e32 v138, v116
	v_mul_f32_e32 v116, 0xbfb8aa3b, v119
	v_exp_f32_e32 v119, v76
	v_mul_f32_e32 v76, 0xbfb8aa3b, v78
	v_exp_f32_e32 v139, v116
	v_mul_f32_e32 v108, 0xbfb8aa3b, v108
	v_exp_f32_e32 v116, v76
	v_mul_f32_e32 v76, 0xbfb8aa3b, v79
	v_exp_f32_e32 v136, v108
	v_mul_f32_e32 v108, 0xbfb8aa3b, v109
	v_exp_f32_e32 v117, v76
	v_mul_f32_e32 v76, 0xbfb8aa3b, v112
	v_exp_f32_e32 v137, v108
	v_mul_f32_e32 v108, 0xbfb8aa3b, v110
	v_exp_f32_e32 v110, v76
	v_mul_f32_e32 v76, 0xbfb8aa3b, v113
	v_exp_f32_e32 v134, v108
	v_mul_f32_e32 v108, 0xbfb8aa3b, v111
	v_exp_f32_e32 v111, v76
	v_mul_f32_e32 v76, 0xbfb8aa3b, v114
	v_exp_f32_e32 v135, v108
	v_mul_f32_e32 v100, 0xbfb8aa3b, v100
	v_exp_f32_e32 v108, v76
	v_mul_f32_e32 v76, 0xbfb8aa3b, v115
	v_exp_f32_e32 v132, v100
	v_mul_f32_e32 v100, 0xbfb8aa3b, v101
	v_exp_f32_e32 v109, v76
	v_mul_f32_e32 v76, 0xbfb8aa3b, v104
	v_exp_f32_e32 v133, v100
	v_mul_f32_e32 v100, 0xbfb8aa3b, v102
	v_exp_f32_e32 v102, v76
	v_mul_f32_e32 v76, 0xbfb8aa3b, v105
	v_mul_f32_e32 v124, 0xbfb8aa3b, v124
	v_exp_f32_e32 v130, v100
	v_mul_f32_e32 v100, 0xbfb8aa3b, v103
	v_exp_f32_e32 v103, v76
	v_mul_f32_e32 v76, 0xbfb8aa3b, v106
	v_exp_f32_e32 v152, v124
	v_mul_f32_e32 v124, 0xbfb8aa3b, v125
	v_exp_f32_e32 v131, v100
	v_mul_f32_e32 v92, 0xbfb8aa3b, v92
	v_exp_f32_e32 v100, v76
	v_mul_f32_e32 v76, 0xbfb8aa3b, v107
	v_exp_f32_e32 v153, v124
	v_mul_f32_e32 v124, 0xbfb8aa3b, v126
	v_exp_f32_e32 v126, v92
	v_mul_f32_e32 v92, 0xbfb8aa3b, v93
	v_exp_f32_e32 v101, v76
	v_mul_f32_e32 v76, 0xbfb8aa3b, v96
	v_exp_f32_e32 v146, v124
	v_mul_f32_e32 v124, 0xbfb8aa3b, v127
	v_exp_f32_e32 v127, v92
	v_mul_f32_e32 v92, 0xbfb8aa3b, v94
	v_exp_f32_e32 v94, v76
	v_mul_f32_e32 v76, 0xbfb8aa3b, v97
	v_exp_f32_e32 v147, v124
	v_mul_f32_e32 v120, 0xbfb8aa3b, v120
	v_exp_f32_e32 v124, v92
	v_mul_f32_e32 v92, 0xbfb8aa3b, v95
	v_exp_f32_e32 v95, v76
	v_mul_f32_e32 v76, 0xbfb8aa3b, v98
	v_exp_f32_e32 v144, v120
	v_mul_f32_e32 v120, 0xbfb8aa3b, v121
	v_exp_f32_e32 v125, v92
	v_mul_f32_e32 v84, 0xbfb8aa3b, v84
	v_exp_f32_e32 v92, v76
	v_mul_f32_e32 v76, 0xbfb8aa3b, v99
	v_exp_f32_e32 v145, v120
	v_mul_f32_e32 v120, 0xbfb8aa3b, v122
	v_exp_f32_e32 v122, v84
	v_mul_f32_e32 v84, 0xbfb8aa3b, v85
	v_exp_f32_e32 v93, v76
	v_mul_f32_e32 v76, 0xbfb8aa3b, v88
	v_exp_f32_e32 v142, v120
	v_mul_f32_e32 v120, 0xbfb8aa3b, v123
	v_exp_f32_e32 v123, v84
	v_mul_f32_e32 v84, 0xbfb8aa3b, v86
	v_exp_f32_e32 v86, v76
	v_mul_f32_e32 v76, 0xbfb8aa3b, v89
	v_exp_f32_e32 v143, v120
	v_exp_f32_e32 v120, v84
	v_mul_f32_e32 v84, 0xbfb8aa3b, v87
	v_exp_f32_e32 v87, v76
	v_mul_f32_e32 v76, 0xbfb8aa3b, v90
	v_exp_f32_e32 v121, v84
	v_exp_f32_e32 v84, v76
	v_mul_f32_e32 v76, 0xbfb8aa3b, v91
	v_exp_f32_e32 v85, v76
	v_mul_f32_e32 v76, 0xbfb8aa3b, v80
	v_exp_f32_e32 v80, v76
	v_mul_f32_e32 v76, 0xbfb8aa3b, v81
	v_exp_f32_e32 v81, v76
	v_mul_f32_e32 v76, 0xbfb8aa3b, v82
	v_exp_f32_e32 v78, v76
	v_mul_f32_e32 v76, 0xbfb8aa3b, v83
	v_mul_f32_e32 v72, 0xbfb8aa3b, v72
	v_exp_f32_e32 v79, v76
	v_exp_f32_e32 v76, v72
	v_mul_f32_e32 v72, 0xbfb8aa3b, v73
	v_exp_f32_e32 v77, v72
	v_mul_f32_e32 v72, 0xbfb8aa3b, v74
	v_exp_f32_e32 v74, v72
	v_mul_f32_e32 v72, 0xbfb8aa3b, v75
	v_mul_f32_e32 v68, 0xbfb8aa3b, v68
	v_exp_f32_e32 v75, v72
	v_exp_f32_e32 v72, v68
	v_mul_f32_e32 v68, 0xbfb8aa3b, v69
	v_exp_f32_e32 v73, v68
	v_mul_f32_e32 v68, 0xbfb8aa3b, v70
	v_exp_f32_e32 v70, v68
	v_mul_f32_e32 v68, 0xbfb8aa3b, v71
	v_mul_f32_e32 v64, 0xbfb8aa3b, v64
	v_exp_f32_e32 v71, v68
	v_exp_f32_e32 v68, v64
	v_mul_f32_e32 v64, 0xbfb8aa3b, v65
	v_exp_f32_e32 v69, v64
	v_mul_f32_e32 v64, 0xbfb8aa3b, v66
	v_mul_f32_e32 v65, 0xbfb8aa3b, v67
	v_exp_f32_e32 v64, v64
	v_exp_f32_e32 v65, v65
	v_mov_b32_e32 v66, v148
	s_lshl_b32 s10, s33, 7
	v_pk_add_f32 v[96:97], v[152:153], 1.0 op_sel_hi:[1,0]
	v_lshrrev_b32_e32 v67, 2, v66
	v_and_or_b32 v67, v67, 12, s10
	v_and_or_b32 v83, v66, 15, s95
	v_or_b32_e32 v82, s81, v67
	v_lshl_or_b32 v98, v83, 11, v151
	v_or_b32_e32 v128, v98, v82
	v_lshl_add_u64 v[88:89], v[128:129], 1, s[12:13]
	v_add_co_u32_e32 v200, vcc, 0x10000, v88
	v_addc_co_u32_e32 v201, vcc, 0, v89, vcc
	global_load_dword v208, v[200:201], off
	v_add_co_u32_e32 v200, vcc, 0x20000, v88
	v_addc_co_u32_e32 v201, vcc, 0, v89, vcc
	global_load_dword v209, v[200:201], off
	v_add_co_u32_e32 v200, vcc, 0x30000, v88
	v_addc_co_u32_e32 v201, vcc, 0, v89, vcc
	global_load_dword v210, v[200:201], off
	v_add_co_u32_e32 v200, vcc, 0x80000, v88
	v_addc_co_u32_e32 v201, vcc, 0, v89, vcc
	global_load_dword v211, v[200:201], off
	v_add_co_u32_e32 v200, vcc, 0x90000, v88
	v_addc_co_u32_e32 v201, vcc, 0, v89, vcc
	global_load_dword v212, v[200:201], off
	v_add_co_u32_e32 v200, vcc, 0xa0000, v88
	v_addc_co_u32_e32 v201, vcc, 0, v89, vcc
	global_load_dword v213, v[200:201], off
	v_add_co_u32_e32 v200, vcc, 0xb0000, v88
	v_addc_co_u32_e32 v201, vcc, 0, v89, vcc
	global_load_dword v214, v[200:201], off
	global_load_dwordx2 v[88:89], v[88:89], off
	v_div_scale_f32 v67, s[72:73], v97, v97, 1.0
	v_lshlrev_b32_e32 v99, 10, v83
	v_or_b32_e32 v66, v82, v99
	s_mov_b32 s10, 1
	s_waitcnt vmcnt(0)
; DI uint2 pk4(float a, float b, float c, float d) { uint2 o; o.x = pk2(a, b); o.y = pk2(c, d); return o; }
; DI float sigmoidf_(float x) { return 1.f / (1.f + __expf(-x)); }
; DI void phaseF(int wv0, PP p, unsigned char* smem) {
;     ...
;             for (int j = 0; j < 4; ++j) acc[ai][0][m][n][j] *= sigmoidf_(acc[ai][1][m][n][j]);
;       __builtin_amdgcn_sched_barrier(0);
;       epi256(wv0, acc, brow, grp * 128, [&](int ai, int bj, int m, int n, int row, int col0, f32x4& v) {
;         if (bj == 0) {
;           const unsigned og = (unsigned)row * 2048u + 1024u + (unsigned)col0, om = (unsigned)row * 1024u + (unsigned)col0;
;           const uint2 gq = *(const uint2*)(MG + og);
;           *(uint2*)(MR + om) = pk4(__uint_as_float(gq.x << 16) * v[0], __uint_as_float(gq.x & 0xffff0000u) * v[1],
;                                    __uint_as_float(gq.y << 16) * v[2], __uint_as_float(gq.y & 0xffff0000u) * v[3]);
;         }
	v_lshlrev_b32_e32 v90, 16, v88
	v_and_b32_e32 v91, 0xffff0000, v88
	v_rcp_f32_e32 v88, v67
	s_nop 0
	v_fma_f32 v104, -v67, v88, 1.0
	v_fmac_f32_e32 v88, v104, v88
	v_div_scale_f32 v104, vcc, 1.0, v97, 1.0
	v_mul_f32_e32 v105, v104, v88
	v_fma_f32 v106, -v67, v105, v104
	v_fmac_f32_e32 v105, v106, v88
	v_fma_f32 v67, -v67, v105, v104
	v_div_fmas_f32 v67, v67, v88, v105
	v_div_fixup_f32 v97, v67, v97, 1.0
	v_div_scale_f32 v67, s[72:73], v96, v96, 1.0
	v_rcp_f32_e32 v88, v67
	s_nop 0
	v_fma_f32 v104, -v67, v88, 1.0
	v_fmac_f32_e32 v88, v104, v88
	v_div_scale_f32 v104, vcc, 1.0, v96, 1.0
	v_mul_f32_e32 v105, v104, v88
	v_fma_f32 v106, -v67, v105, v104
	v_fmac_f32_e32 v105, v106, v88
	v_fma_f32 v67, -v67, v105, v104
	v_div_fmas_f32 v67, v67, v88, v105
	v_div_fixup_f32 v96, v67, v96, 1.0
	v_pk_mul_f32 v[60:61], v[60:61], v[96:97]
	v_lshlrev_b32_e32 v88, 16, v89
	v_pk_mul_f32 v[60:61], v[60:61], v[90:91]
	v_pk_add_f32 v[90:91], v[146:147], 1.0 op_sel_hi:[1,0]
	v_and_b32_e32 v89, 0xffff0000, v89
	v_div_scale_f32 v67, s[72:73], v91, v91, 1.0
	v_rcp_f32_e32 v96, v67
	v_cvt_pk_bf16_f32 v60, v60, v61
	v_fma_f32 v97, -v67, v96, 1.0
	v_fmac_f32_e32 v96, v97, v96
	v_div_scale_f32 v97, vcc, 1.0, v91, 1.0
	v_mul_f32_e32 v104, v97, v96
	v_fma_f32 v105, -v67, v104, v97
	v_fmac_f32_e32 v104, v105, v96
	v_fma_f32 v67, -v67, v104, v97
	v_div_fmas_f32 v67, v67, v96, v104
	v_div_fixup_f32 v91, v67, v91, 1.0
	v_div_scale_f32 v67, s[72:73], v90, v90, 1.0
	v_rcp_f32_e32 v96, v67
	s_nop 0
	v_fma_f32 v97, -v67, v96, 1.0
	v_fmac_f32_e32 v96, v97, v96
	v_div_scale_f32 v97, vcc, 1.0, v90, 1.0
	v_mul_f32_e32 v104, v97, v96
	v_fma_f32 v105, -v67, v104, v97
	v_fmac_f32_e32 v104, v105, v96
	v_fma_f32 v67, -v67, v104, v97
	v_div_fmas_f32 v67, v67, v96, v104
	v_div_fixup_f32 v90, v67, v90, 1.0
	v_pk_mul_f32 v[62:63], v[62:63], v[90:91]
	v_mov_b32_e32 v67, v129
	v_pk_mul_f32 v[62:63], v[62:63], v[88:89]
	v_pk_add_f32 v[90:91], v[144:145], 1.0 op_sel_hi:[1,0]
	v_cvt_pk_bf16_f32 v61, v62, v63
	v_lshl_add_u64 v[62:63], v[66:67], 1, s[14:15]
	global_store_dwordx2 v[62:63], v[60:61], off
	v_or_b32_e32 v62, 16, v82
	v_add_u32_e32 v128, v62, v98
	v_lshl_add_u64 v[66:67], v[128:129], 1, s[12:13]
	global_load_dwordx2 v[66:67], v[66:67], off
	v_div_scale_f32 v61, s[72:73], v91, v91, 1.0
	v_rcp_f32_e32 v63, v61
	v_add_u32_e32 v60, v62, v99
	s_waitcnt vmcnt(0)
	v_lshlrev_b32_e32 v88, 16, v66
	v_and_b32_e32 v89, 0xffff0000, v66
	v_fma_f32 v66, -v61, v63, 1.0
	v_fmac_f32_e32 v63, v66, v63
	v_div_scale_f32 v66, vcc, 1.0, v91, 1.0
	v_mul_f32_e32 v96, v66, v63
	v_fma_f32 v97, -v61, v96, v66
	v_fmac_f32_e32 v96, v97, v63
	v_fma_f32 v61, -v61, v96, v66
	v_div_fmas_f32 v61, v61, v63, v96
	v_div_fixup_f32 v91, v61, v91, 1.0
	v_div_scale_f32 v61, s[72:73], v90, v90, 1.0
	v_rcp_f32_e32 v63, v61
	s_nop 0
	v_fma_f32 v66, -v61, v63, 1.0
	v_fmac_f32_e32 v63, v66, v63
	v_div_scale_f32 v66, vcc, 1.0, v90, 1.0
	v_mul_f32_e32 v96, v66, v63
	v_fma_f32 v97, -v61, v96, v66
	v_fmac_f32_e32 v96, v97, v63
	v_fma_f32 v61, -v61, v96, v66
	v_div_fmas_f32 v61, v61, v63, v96
	v_div_fixup_f32 v90, v61, v90, 1.0
	v_pk_mul_f32 v[56:57], v[56:57], v[90:91]
	v_lshlrev_b32_e32 v66, 16, v67
	v_pk_mul_f32 v[56:57], v[56:57], v[88:89]
	v_pk_add_f32 v[88:89], v[142:143], 1.0 op_sel_hi:[1,0]
	v_and_b32_e32 v67, 0xffff0000, v67
	v_div_scale_f32 v61, s[72:73], v89, v89, 1.0
	v_rcp_f32_e32 v63, v61
	v_cvt_pk_bf16_f32 v56, v56, v57
	v_fma_f32 v90, -v61, v63, 1.0
	v_fmac_f32_e32 v63, v90, v63
	v_div_scale_f32 v90, vcc, 1.0, v89, 1.0
	v_mul_f32_e32 v91, v90, v63
	v_fma_f32 v96, -v61, v91, v90
	v_fmac_f32_e32 v91, v96, v63
	v_fma_f32 v61, -v61, v91, v90
	v_div_fmas_f32 v61, v61, v63, v91
	v_div_fixup_f32 v89, v61, v89, 1.0
	v_div_scale_f32 v61, s[72:73], v88, v88, 1.0
	v_rcp_f32_e32 v63, v61
	s_nop 0
	v_fma_f32 v90, -v61, v63, 1.0
	v_fmac_f32_e32 v63, v90, v63
	v_div_scale_f32 v90, vcc, 1.0, v88, 1.0
	v_mul_f32_e32 v91, v90, v63
	v_fma_f32 v96, -v61, v91, v90
	v_fmac_f32_e32 v91, v96, v63
	v_fma_f32 v61, -v61, v91, v90
	v_div_fmas_f32 v61, v61, v63, v91
	v_div_fixup_f32 v88, v61, v88, 1.0
	v_pk_mul_f32 v[58:59], v[58:59], v[88:89]
	v_mov_b32_e32 v61, v129
	v_pk_mul_f32 v[58:59], v[58:59], v[66:67]
	v_pk_add_f32 v[66:67], v[140:141], 1.0 op_sel_hi:[1,0]
	v_cvt_pk_bf16_f32 v57, v58, v59
	v_lshl_add_u64 v[58:59], v[60:61], 1, s[14:15]
	global_store_dwordx2 v[58:59], v[56:57], off
	v_or_b32_e32 v56, 16, v83
	v_lshl_or_b32 v63, v56, 11, v151
	v_or_b32_e32 v128, v63, v82
	v_lshl_add_u64 v[58:59], v[128:129], 1, s[12:13]
	global_load_dwordx2 v[58:59], v[58:59], off
	v_div_scale_f32 v57, s[72:73], v67, v67, 1.0
	v_lshlrev_b32_e32 v88, 10, v56
	v_or_b32_e32 v56, v88, v82
	v_add_u32_e32 v128, v63, v62
	s_waitcnt vmcnt(0)
; DI uint2 pk4(float a, float b, float c, float d) { uint2 o; o.x = pk2(a, b); o.y = pk2(c, d); return o; }
; DI float sigmoidf_(float x) { return 1.f / (1.f + __expf(-x)); }
; DI void phaseF(int wv0, PP p, unsigned char* smem) {
;     ...
;             for (int j = 0; j < 4; ++j) acc[ai][0][m][n][j] *= sigmoidf_(acc[ai][1][m][n][j]);
;       __builtin_amdgcn_sched_barrier(0);
;       epi256(wv0, acc, brow, grp * 128, [&](int ai, int bj, int m, int n, int row, int col0, f32x4& v) {
;         if (bj == 0) {
;           const unsigned og = (unsigned)row * 2048u + 1024u + (unsigned)col0, om = (unsigned)row * 1024u + (unsigned)col0;
;           const uint2 gq = *(const uint2*)(MG + og);
;           *(uint2*)(MR + om) = pk4(__uint_as_float(gq.x << 16) * v[0], __uint_as_float(gq.x & 0xffff0000u) * v[1],
;                                    __uint_as_float(gq.y << 16) * v[2], __uint_as_float(gq.y & 0xffff0000u) * v[3]);
;         }
	v_lshlrev_b32_e32 v60, 16, v58
	v_and_b32_e32 v61, 0xffff0000, v58
	v_rcp_f32_e32 v58, v57
	s_nop 0
	v_fma_f32 v89, -v57, v58, 1.0
	v_fmac_f32_e32 v58, v89, v58
	v_div_scale_f32 v89, vcc, 1.0, v67, 1.0
	v_mul_f32_e32 v90, v89, v58
	v_fma_f32 v91, -v57, v90, v89
	v_fmac_f32_e32 v90, v91, v58
	v_fma_f32 v57, -v57, v90, v89
	v_div_fmas_f32 v57, v57, v58, v90
	v_div_fixup_f32 v67, v57, v67, 1.0
	v_div_scale_f32 v57, s[72:73], v66, v66, 1.0
	v_rcp_f32_e32 v58, v57
	s_nop 0
	v_fma_f32 v89, -v57, v58, 1.0
	v_fmac_f32_e32 v58, v89, v58
	v_div_scale_f32 v89, vcc, 1.0, v66, 1.0
	v_mul_f32_e32 v90, v89, v58
	v_fma_f32 v91, -v57, v90, v89
	v_fmac_f32_e32 v90, v91, v58
	v_fma_f32 v57, -v57, v90, v89
	v_div_fmas_f32 v57, v57, v58, v90
	v_div_fixup_f32 v66, v57, v66, 1.0
	v_pk_mul_f32 v[52:53], v[52:53], v[66:67]
	v_lshlrev_b32_e32 v58, 16, v59
	v_pk_mul_f32 v[52:53], v[52:53], v[60:61]
	v_pk_add_f32 v[60:61], v[138:139], 1.0 op_sel_hi:[1,0]
	v_and_b32_e32 v59, 0xffff0000, v59
	v_div_scale_f32 v57, s[72:73], v61, v61, 1.0
	v_rcp_f32_e32 v66, v57
	v_cvt_pk_bf16_f32 v52, v52, v53
	v_fma_f32 v67, -v57, v66, 1.0
	v_fmac_f32_e32 v66, v67, v66
	v_div_scale_f32 v67, vcc, 1.0, v61, 1.0
	v_mul_f32_e32 v89, v67, v66
	v_fma_f32 v90, -v57, v89, v67
	v_fmac_f32_e32 v89, v90, v66
	v_fma_f32 v57, -v57, v89, v67
	v_div_fmas_f32 v57, v57, v66, v89
	v_div_fixup_f32 v61, v57, v61, 1.0
	v_div_scale_f32 v57, s[72:73], v60, v60, 1.0
	v_rcp_f32_e32 v66, v57
	s_nop 0
	v_fma_f32 v67, -v57, v66, 1.0
	v_fmac_f32_e32 v66, v67, v66
	v_div_scale_f32 v67, vcc, 1.0, v60, 1.0
	v_mul_f32_e32 v89, v67, v66
	v_fma_f32 v90, -v57, v89, v67
	v_fmac_f32_e32 v89, v90, v66
	v_fma_f32 v57, -v57, v89, v67
	v_div_fmas_f32 v57, v57, v66, v89
	v_div_fixup_f32 v60, v57, v60, 1.0
	v_pk_mul_f32 v[54:55], v[54:55], v[60:61]
	v_mov_b32_e32 v57, v129
	v_pk_mul_f32 v[54:55], v[54:55], v[58:59]
	v_pk_add_f32 v[58:59], v[136:137], 1.0 op_sel_hi:[1,0]
	v_cvt_pk_bf16_f32 v53, v54, v55
	v_lshl_add_u64 v[54:55], v[56:57], 1, s[14:15]
	global_store_dwordx2 v[54:55], v[52:53], off
	v_lshl_add_u64 v[54:55], v[128:129], 1, s[12:13]
	global_load_dwordx2 v[54:55], v[54:55], off
	v_div_scale_f32 v53, s[72:73], v59, v59, 1.0
	v_add_u32_e32 v52, v62, v88
	s_waitcnt vmcnt(0)
	v_lshlrev_b32_e32 v56, 16, v54
	v_and_b32_e32 v57, 0xffff0000, v54
	v_rcp_f32_e32 v54, v53
	s_nop 0
	v_fma_f32 v60, -v53, v54, 1.0
	v_fmac_f32_e32 v54, v60, v54
	v_div_scale_f32 v60, vcc, 1.0, v59, 1.0
	v_mul_f32_e32 v61, v60, v54
	v_fma_f32 v63, -v53, v61, v60
	v_fmac_f32_e32 v61, v63, v54
	v_fma_f32 v53, -v53, v61, v60
	v_div_fmas_f32 v53, v53, v54, v61
	v_div_fixup_f32 v59, v53, v59, 1.0
	v_div_scale_f32 v53, s[72:73], v58, v58, 1.0
	v_rcp_f32_e32 v54, v53
	s_nop 0
	v_fma_f32 v60, -v53, v54, 1.0
	v_fmac_f32_e32 v54, v60, v54
	v_div_scale_f32 v60, vcc, 1.0, v58, 1.0
	v_mul_f32_e32 v61, v60, v54
	v_fma_f32 v63, -v53, v61, v60
	v_fmac_f32_e32 v61, v63, v54
	v_fma_f32 v53, -v53, v61, v60
	v_div_fmas_f32 v53, v53, v54, v61
	v_div_fixup_f32 v58, v53, v58, 1.0
	v_pk_mul_f32 v[48:49], v[48:49], v[58:59]
	v_lshlrev_b32_e32 v54, 16, v55
	v_pk_mul_f32 v[48:49], v[48:49], v[56:57]
	v_pk_add_f32 v[56:57], v[134:135], 1.0 op_sel_hi:[1,0]
	v_and_b32_e32 v55, 0xffff0000, v55
	v_div_scale_f32 v53, s[72:73], v57, v57, 1.0
	v_rcp_f32_e32 v58, v53
	v_cvt_pk_bf16_f32 v48, v48, v49
	v_fma_f32 v59, -v53, v58, 1.0
	v_fmac_f32_e32 v58, v59, v58
	v_div_scale_f32 v59, vcc, 1.0, v57, 1.0
	v_mul_f32_e32 v60, v59, v58
	v_fma_f32 v61, -v53, v60, v59
	v_fmac_f32_e32 v60, v61, v58
	v_fma_f32 v53, -v53, v60, v59
	v_div_fmas_f32 v53, v53, v58, v60
	v_div_fixup_f32 v57, v53, v57, 1.0
	v_div_scale_f32 v53, s[72:73], v56, v56, 1.0
	v_rcp_f32_e32 v58, v53
	s_nop 0
	v_fma_f32 v59, -v53, v58, 1.0
	v_fmac_f32_e32 v58, v59, v58
	v_div_scale_f32 v59, vcc, 1.0, v56, 1.0
	v_mul_f32_e32 v60, v59, v58
	v_fma_f32 v61, -v53, v60, v59
	v_fmac_f32_e32 v60, v61, v58
	v_fma_f32 v53, -v53, v60, v59
	v_div_fmas_f32 v53, v53, v58, v60
	v_div_fixup_f32 v56, v53, v56, 1.0
	v_pk_mul_f32 v[50:51], v[50:51], v[56:57]
	v_mov_b32_e32 v53, v129
	v_pk_mul_f32 v[50:51], v[50:51], v[54:55]
	s_nop 0
	v_cvt_pk_bf16_f32 v49, v50, v51
	v_lshl_add_u64 v[50:51], v[52:53], 1, s[14:15]
	global_store_dwordx2 v[50:51], v[48:49], off
	v_or_b32_e32 v48, 32, v83
	v_lshl_or_b32 v56, v48, 11, v151
	v_or_b32_e32 v128, v56, v82
	v_lshl_add_u64 v[50:51], v[128:129], 1, s[12:13]
	global_load_dwordx2 v[50:51], v[50:51], off
	v_pk_add_f32 v[54:55], v[132:133], 1.0 op_sel_hi:[1,0]
	v_lshlrev_b32_e32 v57, 10, v48
	v_div_scale_f32 v49, s[72:73], v55, v55, 1.0
	v_or_b32_e32 v48, v57, v82
	v_add_u32_e32 v128, v56, v62
	s_waitcnt vmcnt(0)
; DI uint2 pk4(float a, float b, float c, float d) { uint2 o; o.x = pk2(a, b); o.y = pk2(c, d); return o; }
; DI float sigmoidf_(float x) { return 1.f / (1.f + __expf(-x)); }
; DI void phaseF(int wv0, PP p, unsigned char* smem) {
;     ...
;             for (int j = 0; j < 4; ++j) acc[ai][0][m][n][j] *= sigmoidf_(acc[ai][1][m][n][j]);
;       __builtin_amdgcn_sched_barrier(0);
;       epi256(wv0, acc, brow, grp * 128, [&](int ai, int bj, int m, int n, int row, int col0, f32x4& v) {
;         if (bj == 0) {
;           const unsigned og = (unsigned)row * 2048u + 1024u + (unsigned)col0, om = (unsigned)row * 1024u + (unsigned)col0;
;           const uint2 gq = *(const uint2*)(MG + og);
;           *(uint2*)(MR + om) = pk4(__uint_as_float(gq.x << 16) * v[0], __uint_as_float(gq.x & 0xffff0000u) * v[1],
;                                    __uint_as_float(gq.y << 16) * v[2], __uint_as_float(gq.y & 0xffff0000u) * v[3]);
;         }
	v_lshlrev_b32_e32 v52, 16, v50
	v_and_b32_e32 v53, 0xffff0000, v50
	v_rcp_f32_e32 v50, v49
	s_nop 0
	v_fma_f32 v58, -v49, v50, 1.0
	v_fmac_f32_e32 v50, v58, v50
	v_div_scale_f32 v58, vcc, 1.0, v55, 1.0
	v_mul_f32_e32 v59, v58, v50
	v_fma_f32 v60, -v49, v59, v58
	v_fmac_f32_e32 v59, v60, v50
	v_fma_f32 v49, -v49, v59, v58
	v_div_fmas_f32 v49, v49, v50, v59
	v_div_fixup_f32 v55, v49, v55, 1.0
	v_div_scale_f32 v49, s[72:73], v54, v54, 1.0
	v_rcp_f32_e32 v50, v49
	s_nop 0
	v_fma_f32 v58, -v49, v50, 1.0
	v_fmac_f32_e32 v50, v58, v50
	v_div_scale_f32 v58, vcc, 1.0, v54, 1.0
	v_mul_f32_e32 v59, v58, v50
	v_fma_f32 v60, -v49, v59, v58
	v_fmac_f32_e32 v59, v60, v50
	v_fma_f32 v49, -v49, v59, v58
	v_div_fmas_f32 v49, v49, v50, v59
	v_div_fixup_f32 v54, v49, v54, 1.0
	v_pk_mul_f32 v[44:45], v[44:45], v[54:55]
	v_lshlrev_b32_e32 v50, 16, v51
	v_pk_mul_f32 v[44:45], v[44:45], v[52:53]
	v_pk_add_f32 v[52:53], v[130:131], 1.0 op_sel_hi:[1,0]
	v_and_b32_e32 v51, 0xffff0000, v51
	v_div_scale_f32 v49, s[72:73], v53, v53, 1.0
	v_rcp_f32_e32 v54, v49
	v_cvt_pk_bf16_f32 v44, v44, v45
	v_fma_f32 v55, -v49, v54, 1.0
	v_fmac_f32_e32 v54, v55, v54
	v_div_scale_f32 v55, vcc, 1.0, v53, 1.0
	v_mul_f32_e32 v58, v55, v54
	v_fma_f32 v59, -v49, v58, v55
	v_fmac_f32_e32 v58, v59, v54
	v_fma_f32 v49, -v49, v58, v55
	v_div_fmas_f32 v49, v49, v54, v58
	v_div_fixup_f32 v53, v49, v53, 1.0
	v_div_scale_f32 v49, s[72:73], v52, v52, 1.0
	v_rcp_f32_e32 v54, v49
	s_nop 0
	v_fma_f32 v55, -v49, v54, 1.0
	v_fmac_f32_e32 v54, v55, v54
	v_div_scale_f32 v55, vcc, 1.0, v52, 1.0
	v_mul_f32_e32 v58, v55, v54
	v_fma_f32 v59, -v49, v58, v55
	v_fmac_f32_e32 v58, v59, v54
	v_fma_f32 v49, -v49, v58, v55
	v_div_fmas_f32 v49, v49, v54, v58
	v_div_fixup_f32 v52, v49, v52, 1.0
	v_pk_mul_f32 v[46:47], v[46:47], v[52:53]
	v_mov_b32_e32 v49, v129
	v_pk_mul_f32 v[46:47], v[46:47], v[50:51]
	v_pk_add_f32 v[50:51], v[126:127], 1.0 op_sel_hi:[1,0]
	v_cvt_pk_bf16_f32 v45, v46, v47
	v_lshl_add_u64 v[46:47], v[48:49], 1, s[14:15]
	global_store_dwordx2 v[46:47], v[44:45], off
	v_lshl_add_u64 v[46:47], v[128:129], 1, s[12:13]
	global_load_dwordx2 v[46:47], v[46:47], off
	v_div_scale_f32 v45, s[72:73], v51, v51, 1.0
	v_add_u32_e32 v44, v62, v57
	s_waitcnt vmcnt(0)
	v_lshlrev_b32_e32 v48, 16, v46
	v_and_b32_e32 v49, 0xffff0000, v46
	v_rcp_f32_e32 v46, v45
	s_nop 0
	v_fma_f32 v52, -v45, v46, 1.0
	v_fmac_f32_e32 v46, v52, v46
	v_div_scale_f32 v52, vcc, 1.0, v51, 1.0
	v_mul_f32_e32 v53, v52, v46
	v_fma_f32 v54, -v45, v53, v52
	v_fmac_f32_e32 v53, v54, v46
	v_fma_f32 v45, -v45, v53, v52
	v_div_fmas_f32 v45, v45, v46, v53
	v_div_fixup_f32 v51, v45, v51, 1.0
	v_div_scale_f32 v45, s[72:73], v50, v50, 1.0
	v_rcp_f32_e32 v46, v45
	s_nop 0
	v_fma_f32 v52, -v45, v46, 1.0
	v_fmac_f32_e32 v46, v52, v46
	v_div_scale_f32 v52, vcc, 1.0, v50, 1.0
	v_mul_f32_e32 v53, v52, v46
	v_fma_f32 v54, -v45, v53, v52
	v_fmac_f32_e32 v53, v54, v46
	v_fma_f32 v45, -v45, v53, v52
	v_div_fmas_f32 v45, v45, v46, v53
	v_div_fixup_f32 v50, v45, v50, 1.0
	v_pk_mul_f32 v[40:41], v[40:41], v[50:51]
	v_lshlrev_b32_e32 v46, 16, v47
	v_pk_mul_f32 v[40:41], v[40:41], v[48:49]
	v_pk_add_f32 v[48:49], v[124:125], 1.0 op_sel_hi:[1,0]
	v_and_b32_e32 v47, 0xffff0000, v47
	v_div_scale_f32 v45, s[72:73], v49, v49, 1.0
	v_rcp_f32_e32 v50, v45
	v_cvt_pk_bf16_f32 v40, v40, v41
	v_fma_f32 v51, -v45, v50, 1.0
	v_fmac_f32_e32 v50, v51, v50
	v_div_scale_f32 v51, vcc, 1.0, v49, 1.0
	v_mul_f32_e32 v52, v51, v50
	v_fma_f32 v53, -v45, v52, v51
	v_fmac_f32_e32 v52, v53, v50
	v_fma_f32 v45, -v45, v52, v51
	v_div_fmas_f32 v45, v45, v50, v52
	v_div_fixup_f32 v49, v45, v49, 1.0
	v_div_scale_f32 v45, s[72:73], v48, v48, 1.0
	v_rcp_f32_e32 v50, v45
	s_nop 0
	v_fma_f32 v51, -v45, v50, 1.0
	v_fmac_f32_e32 v50, v51, v50
	v_div_scale_f32 v51, vcc, 1.0, v48, 1.0
	v_mul_f32_e32 v52, v51, v50
	v_fma_f32 v53, -v45, v52, v51
	v_fmac_f32_e32 v52, v53, v50
	v_fma_f32 v45, -v45, v52, v51
	v_div_fmas_f32 v45, v45, v50, v52
	v_div_fixup_f32 v48, v45, v48, 1.0
	v_pk_mul_f32 v[42:43], v[42:43], v[48:49]
	v_mov_b32_e32 v45, v129
	v_pk_mul_f32 v[42:43], v[42:43], v[46:47]
	v_pk_add_f32 v[46:47], v[122:123], 1.0 op_sel_hi:[1,0]
	v_cvt_pk_bf16_f32 v41, v42, v43
	v_lshl_add_u64 v[42:43], v[44:45], 1, s[14:15]
	global_store_dwordx2 v[42:43], v[40:41], off
	v_or_b32_e32 v40, 48, v83
	v_lshl_or_b32 v48, v40, 11, v151
	v_or_b32_e32 v128, v48, v82
	v_lshl_add_u64 v[42:43], v[128:129], 1, s[12:13]
	global_load_dwordx2 v[42:43], v[42:43], off
	v_div_scale_f32 v41, s[72:73], v47, v47, 1.0
	v_lshlrev_b32_e32 v49, 10, v40
	v_or_b32_e32 v40, v49, v82
	v_add_u32_e32 v128, v48, v62
	s_waitcnt vmcnt(0)
; DI uint2 pk4(float a, float b, float c, float d) { uint2 o; o.x = pk2(a, b); o.y = pk2(c, d); return o; }
; DI float sigmoidf_(float x) { return 1.f / (1.f + __expf(-x)); }
; DI void phaseF(int wv0, PP p, unsigned char* smem) {
;     ...
;             for (int j = 0; j < 4; ++j) acc[ai][0][m][n][j] *= sigmoidf_(acc[ai][1][m][n][j]);
;       __builtin_amdgcn_sched_barrier(0);
;       epi256(wv0, acc, brow, grp * 128, [&](int ai, int bj, int m, int n, int row, int col0, f32x4& v) {
;         if (bj == 0) {
;           const unsigned og = (unsigned)row * 2048u + 1024u + (unsigned)col0, om = (unsigned)row * 1024u + (unsigned)col0;
;           const uint2 gq = *(const uint2*)(MG + og);
;           *(uint2*)(MR + om) = pk4(__uint_as_float(gq.x << 16) * v[0], __uint_as_float(gq.x & 0xffff0000u) * v[1],
;                                    __uint_as_float(gq.y << 16) * v[2], __uint_as_float(gq.y & 0xffff0000u) * v[3]);
;         }
	v_lshlrev_b32_e32 v44, 16, v42
	v_and_b32_e32 v45, 0xffff0000, v42
	v_rcp_f32_e32 v42, v41
	s_nop 0
	v_fma_f32 v50, -v41, v42, 1.0
	v_fmac_f32_e32 v42, v50, v42
	v_div_scale_f32 v50, vcc, 1.0, v47, 1.0
	v_mul_f32_e32 v51, v50, v42
	v_fma_f32 v52, -v41, v51, v50
	v_fmac_f32_e32 v51, v52, v42
	v_fma_f32 v41, -v41, v51, v50
	v_div_fmas_f32 v41, v41, v42, v51
	v_div_fixup_f32 v47, v41, v47, 1.0
	v_div_scale_f32 v41, s[72:73], v46, v46, 1.0
	v_rcp_f32_e32 v42, v41
	s_nop 0
	v_fma_f32 v50, -v41, v42, 1.0
	v_fmac_f32_e32 v42, v50, v42
	v_div_scale_f32 v50, vcc, 1.0, v46, 1.0
	v_mul_f32_e32 v51, v50, v42
	v_fma_f32 v52, -v41, v51, v50
	v_fmac_f32_e32 v51, v52, v42
	v_fma_f32 v41, -v41, v51, v50
	v_div_fmas_f32 v41, v41, v42, v51
	v_div_fixup_f32 v46, v41, v46, 1.0
	v_pk_mul_f32 v[36:37], v[36:37], v[46:47]
	v_lshlrev_b32_e32 v42, 16, v43
	v_pk_mul_f32 v[36:37], v[36:37], v[44:45]
	v_pk_add_f32 v[44:45], v[120:121], 1.0 op_sel_hi:[1,0]
	v_and_b32_e32 v43, 0xffff0000, v43
	v_div_scale_f32 v41, s[72:73], v45, v45, 1.0
	v_rcp_f32_e32 v46, v41
	v_cvt_pk_bf16_f32 v36, v36, v37
	v_fma_f32 v47, -v41, v46, 1.0
	v_fmac_f32_e32 v46, v47, v46
	v_div_scale_f32 v47, vcc, 1.0, v45, 1.0
	v_mul_f32_e32 v50, v47, v46
	v_fma_f32 v51, -v41, v50, v47
	v_fmac_f32_e32 v50, v51, v46
	v_fma_f32 v41, -v41, v50, v47
	v_div_fmas_f32 v41, v41, v46, v50
	v_div_fixup_f32 v45, v41, v45, 1.0
	v_div_scale_f32 v41, s[72:73], v44, v44, 1.0
	v_rcp_f32_e32 v46, v41
	s_nop 0
	v_fma_f32 v47, -v41, v46, 1.0
	v_fmac_f32_e32 v46, v47, v46
	v_div_scale_f32 v47, vcc, 1.0, v44, 1.0
	v_mul_f32_e32 v50, v47, v46
	v_fma_f32 v51, -v41, v50, v47
	v_fmac_f32_e32 v50, v51, v46
	v_fma_f32 v41, -v41, v50, v47
	v_div_fmas_f32 v41, v41, v46, v50
	v_div_fixup_f32 v44, v41, v44, 1.0
	v_pk_mul_f32 v[38:39], v[38:39], v[44:45]
	v_mov_b32_e32 v41, v129
	v_pk_mul_f32 v[38:39], v[38:39], v[42:43]
	v_pk_add_f32 v[42:43], v[118:119], 1.0 op_sel_hi:[1,0]
	v_cvt_pk_bf16_f32 v37, v38, v39
	v_lshl_add_u64 v[38:39], v[40:41], 1, s[14:15]
	global_store_dwordx2 v[38:39], v[36:37], off
	v_lshl_add_u64 v[38:39], v[128:129], 1, s[12:13]
	global_load_dwordx2 v[38:39], v[38:39], off
	v_div_scale_f32 v37, s[72:73], v43, v43, 1.0
	v_add_u32_e32 v36, v62, v49
	s_waitcnt vmcnt(0)
	v_lshlrev_b32_e32 v40, 16, v38
	v_and_b32_e32 v41, 0xffff0000, v38
	v_rcp_f32_e32 v38, v37
	s_nop 0
	v_fma_f32 v44, -v37, v38, 1.0
	v_fmac_f32_e32 v38, v44, v38
	v_div_scale_f32 v44, vcc, 1.0, v43, 1.0
	v_mul_f32_e32 v45, v44, v38
	v_fma_f32 v46, -v37, v45, v44
	v_fmac_f32_e32 v45, v46, v38
	v_fma_f32 v37, -v37, v45, v44
	v_div_fmas_f32 v37, v37, v38, v45
	v_div_fixup_f32 v43, v37, v43, 1.0
	v_div_scale_f32 v37, s[72:73], v42, v42, 1.0
	v_rcp_f32_e32 v38, v37
	s_nop 0
	v_fma_f32 v44, -v37, v38, 1.0
	v_fmac_f32_e32 v38, v44, v38
	v_div_scale_f32 v44, vcc, 1.0, v42, 1.0
	v_mul_f32_e32 v45, v44, v38
	v_fma_f32 v46, -v37, v45, v44
	v_fmac_f32_e32 v45, v46, v38
	v_fma_f32 v37, -v37, v45, v44
	v_div_fmas_f32 v37, v37, v38, v45
	v_div_fixup_f32 v42, v37, v42, 1.0
	v_pk_mul_f32 v[32:33], v[32:33], v[42:43]
	v_lshlrev_b32_e32 v38, 16, v39
	v_pk_mul_f32 v[32:33], v[32:33], v[40:41]
	v_pk_add_f32 v[40:41], v[116:117], 1.0 op_sel_hi:[1,0]
	v_and_b32_e32 v39, 0xffff0000, v39
	v_div_scale_f32 v37, s[72:73], v41, v41, 1.0
	v_rcp_f32_e32 v42, v37
	v_cvt_pk_bf16_f32 v32, v32, v33
	v_fma_f32 v43, -v37, v42, 1.0
	v_fmac_f32_e32 v42, v43, v42
	v_div_scale_f32 v43, vcc, 1.0, v41, 1.0
	v_mul_f32_e32 v44, v43, v42
	v_fma_f32 v45, -v37, v44, v43
	v_fmac_f32_e32 v44, v45, v42
	v_fma_f32 v37, -v37, v44, v43
	v_div_fmas_f32 v37, v37, v42, v44
	v_div_fixup_f32 v41, v37, v41, 1.0
	v_div_scale_f32 v37, s[72:73], v40, v40, 1.0
	v_rcp_f32_e32 v42, v37
	s_nop 0
	v_fma_f32 v43, -v37, v42, 1.0
	v_fmac_f32_e32 v42, v43, v42
	v_div_scale_f32 v43, vcc, 1.0, v40, 1.0
	v_mul_f32_e32 v44, v43, v42
	v_fma_f32 v45, -v37, v44, v43
	v_fmac_f32_e32 v44, v45, v42
	v_fma_f32 v37, -v37, v44, v43
	v_div_fmas_f32 v37, v37, v42, v44
	v_div_fixup_f32 v40, v37, v40, 1.0
	v_pk_mul_f32 v[34:35], v[34:35], v[40:41]
	v_mov_b32_e32 v37, v129
	v_pk_mul_f32 v[34:35], v[34:35], v[38:39]
	s_nop 0
	v_cvt_pk_bf16_f32 v33, v34, v35
	v_lshl_add_u64 v[34:35], v[36:37], 1, s[14:15]
	global_store_dwordx2 v[34:35], v[32:33], off
	v_add_u32_e32 v32, 0x80, v83
	v_lshl_or_b32 v40, v32, 11, v151
	v_or_b32_e32 v128, v40, v82
	v_lshl_add_u64 v[34:35], v[128:129], 1, s[12:13]
	global_load_dwordx2 v[34:35], v[34:35], off
	v_pk_add_f32 v[38:39], v[110:111], 1.0 op_sel_hi:[1,0]
	v_lshlrev_b32_e32 v41, 10, v32
	v_div_scale_f32 v33, s[72:73], v39, v39, 1.0
	v_or_b32_e32 v32, v41, v82
	v_add_u32_e32 v128, v40, v62
	s_waitcnt vmcnt(0)
; DI uint2 pk4(float a, float b, float c, float d) { uint2 o; o.x = pk2(a, b); o.y = pk2(c, d); return o; }
; DI float sigmoidf_(float x) { return 1.f / (1.f + __expf(-x)); }
; DI void phaseF(int wv0, PP p, unsigned char* smem) {
;     ...
;             for (int j = 0; j < 4; ++j) acc[ai][0][m][n][j] *= sigmoidf_(acc[ai][1][m][n][j]);
;       __builtin_amdgcn_sched_barrier(0);
;       epi256(wv0, acc, brow, grp * 128, [&](int ai, int bj, int m, int n, int row, int col0, f32x4& v) {
;         if (bj == 0) {
;           const unsigned og = (unsigned)row * 2048u + 1024u + (unsigned)col0, om = (unsigned)row * 1024u + (unsigned)col0;
;           const uint2 gq = *(const uint2*)(MG + og);
;           *(uint2*)(MR + om) = pk4(__uint_as_float(gq.x << 16) * v[0], __uint_as_float(gq.x & 0xffff0000u) * v[1],
;                                    __uint_as_float(gq.y << 16) * v[2], __uint_as_float(gq.y & 0xffff0000u) * v[3]);
;         }
	v_lshlrev_b32_e32 v36, 16, v34
	v_and_b32_e32 v37, 0xffff0000, v34
	v_rcp_f32_e32 v34, v33
	s_nop 0
	v_fma_f32 v42, -v33, v34, 1.0
	v_fmac_f32_e32 v34, v42, v34
	v_div_scale_f32 v42, vcc, 1.0, v39, 1.0
	v_mul_f32_e32 v43, v42, v34
	v_fma_f32 v44, -v33, v43, v42
	v_fmac_f32_e32 v43, v44, v34
	v_fma_f32 v33, -v33, v43, v42
	v_div_fmas_f32 v33, v33, v34, v43
	v_div_fixup_f32 v39, v33, v39, 1.0
	v_div_scale_f32 v33, s[72:73], v38, v38, 1.0
	v_rcp_f32_e32 v34, v33
	s_nop 0
	v_fma_f32 v42, -v33, v34, 1.0
	v_fmac_f32_e32 v34, v42, v34
	v_div_scale_f32 v42, vcc, 1.0, v38, 1.0
	v_mul_f32_e32 v43, v42, v34
	v_fma_f32 v44, -v33, v43, v42
	v_fmac_f32_e32 v43, v44, v34
	v_fma_f32 v33, -v33, v43, v42
	v_div_fmas_f32 v33, v33, v34, v43
	v_div_fixup_f32 v38, v33, v38, 1.0
	v_pk_mul_f32 v[28:29], v[28:29], v[38:39]
	v_lshlrev_b32_e32 v34, 16, v35
	v_pk_mul_f32 v[28:29], v[28:29], v[36:37]
	v_pk_add_f32 v[36:37], v[108:109], 1.0 op_sel_hi:[1,0]
	v_and_b32_e32 v35, 0xffff0000, v35
	v_div_scale_f32 v33, s[72:73], v37, v37, 1.0
	v_rcp_f32_e32 v38, v33
	v_cvt_pk_bf16_f32 v28, v28, v29
	v_fma_f32 v39, -v33, v38, 1.0
	v_fmac_f32_e32 v38, v39, v38
	v_div_scale_f32 v39, vcc, 1.0, v37, 1.0
	v_mul_f32_e32 v42, v39, v38
	v_fma_f32 v43, -v33, v42, v39
	v_fmac_f32_e32 v42, v43, v38
	v_fma_f32 v33, -v33, v42, v39
	v_div_fmas_f32 v33, v33, v38, v42
	v_div_fixup_f32 v37, v33, v37, 1.0
	v_div_scale_f32 v33, s[72:73], v36, v36, 1.0
	v_rcp_f32_e32 v38, v33
	s_nop 0
	v_fma_f32 v39, -v33, v38, 1.0
	v_fmac_f32_e32 v38, v39, v38
	v_div_scale_f32 v39, vcc, 1.0, v36, 1.0
	v_mul_f32_e32 v42, v39, v38
	v_fma_f32 v43, -v33, v42, v39
	v_fmac_f32_e32 v42, v43, v38
	v_fma_f32 v33, -v33, v42, v39
	v_div_fmas_f32 v33, v33, v38, v42
	v_div_fixup_f32 v36, v33, v36, 1.0
	v_pk_mul_f32 v[30:31], v[30:31], v[36:37]
	v_mov_b32_e32 v33, v129
	v_pk_mul_f32 v[30:31], v[30:31], v[34:35]
	v_pk_add_f32 v[34:35], v[102:103], 1.0 op_sel_hi:[1,0]
	v_cvt_pk_bf16_f32 v29, v30, v31
	v_lshl_add_u64 v[30:31], v[32:33], 1, s[14:15]
	global_store_dwordx2 v[30:31], v[28:29], off
	v_lshl_add_u64 v[30:31], v[128:129], 1, s[12:13]
	global_load_dwordx2 v[30:31], v[30:31], off
	v_div_scale_f32 v29, s[72:73], v35, v35, 1.0
	v_add_u32_e32 v28, v62, v41
	s_waitcnt vmcnt(0)
	v_lshlrev_b32_e32 v32, 16, v30
	v_and_b32_e32 v33, 0xffff0000, v30
	v_rcp_f32_e32 v30, v29
	s_nop 0
	v_fma_f32 v36, -v29, v30, 1.0
	v_fmac_f32_e32 v30, v36, v30
	v_div_scale_f32 v36, vcc, 1.0, v35, 1.0
	v_mul_f32_e32 v37, v36, v30
	v_fma_f32 v38, -v29, v37, v36
	v_fmac_f32_e32 v37, v38, v30
	v_fma_f32 v29, -v29, v37, v36
	v_div_fmas_f32 v29, v29, v30, v37
	v_div_fixup_f32 v35, v29, v35, 1.0
	v_div_scale_f32 v29, s[72:73], v34, v34, 1.0
	v_rcp_f32_e32 v30, v29
	s_nop 0
	v_fma_f32 v36, -v29, v30, 1.0
	v_fmac_f32_e32 v30, v36, v30
	v_div_scale_f32 v36, vcc, 1.0, v34, 1.0
	v_mul_f32_e32 v37, v36, v30
	v_fma_f32 v38, -v29, v37, v36
	v_fmac_f32_e32 v37, v38, v30
	v_fma_f32 v29, -v29, v37, v36
	v_div_fmas_f32 v29, v29, v30, v37
	v_div_fixup_f32 v34, v29, v34, 1.0
	v_pk_mul_f32 v[24:25], v[24:25], v[34:35]
	v_lshlrev_b32_e32 v30, 16, v31
	v_pk_mul_f32 v[24:25], v[24:25], v[32:33]
	v_pk_add_f32 v[32:33], v[100:101], 1.0 op_sel_hi:[1,0]
	v_and_b32_e32 v31, 0xffff0000, v31
	v_div_scale_f32 v29, s[72:73], v33, v33, 1.0
	v_rcp_f32_e32 v34, v29
	v_cvt_pk_bf16_f32 v24, v24, v25
	v_fma_f32 v35, -v29, v34, 1.0
	v_fmac_f32_e32 v34, v35, v34
	v_div_scale_f32 v35, vcc, 1.0, v33, 1.0
	v_mul_f32_e32 v36, v35, v34
	v_fma_f32 v37, -v29, v36, v35
	v_fmac_f32_e32 v36, v37, v34
	v_fma_f32 v29, -v29, v36, v35
	v_div_fmas_f32 v29, v29, v34, v36
	v_div_fixup_f32 v33, v29, v33, 1.0
	v_div_scale_f32 v29, s[72:73], v32, v32, 1.0
	v_rcp_f32_e32 v34, v29
	s_nop 0
	v_fma_f32 v35, -v29, v34, 1.0
	v_fmac_f32_e32 v34, v35, v34
	v_div_scale_f32 v35, vcc, 1.0, v32, 1.0
	v_mul_f32_e32 v36, v35, v34
	v_fma_f32 v37, -v29, v36, v35
	v_fmac_f32_e32 v36, v37, v34
	v_fma_f32 v29, -v29, v36, v35
	v_div_fmas_f32 v29, v29, v34, v36
	v_div_fixup_f32 v32, v29, v32, 1.0
	v_pk_mul_f32 v[26:27], v[26:27], v[32:33]
	v_mov_b32_e32 v29, v129
	v_pk_mul_f32 v[26:27], v[26:27], v[30:31]
	v_pk_add_f32 v[30:31], v[94:95], 1.0 op_sel_hi:[1,0]
	v_cvt_pk_bf16_f32 v25, v26, v27
	v_lshl_add_u64 v[26:27], v[28:29], 1, s[14:15]
	global_store_dwordx2 v[26:27], v[24:25], off
	v_add_u32_e32 v24, 0x90, v83
	v_lshl_or_b32 v32, v24, 11, v151
	v_or_b32_e32 v128, v32, v82
	v_lshl_add_u64 v[26:27], v[128:129], 1, s[12:13]
	global_load_dwordx2 v[26:27], v[26:27], off
	v_div_scale_f32 v25, s[72:73], v31, v31, 1.0
	v_lshlrev_b32_e32 v33, 10, v24
	v_or_b32_e32 v24, v33, v82
	v_add_u32_e32 v128, v32, v62
	s_waitcnt vmcnt(0)
; DI uint2 pk4(float a, float b, float c, float d) { uint2 o; o.x = pk2(a, b); o.y = pk2(c, d); return o; }
; DI float sigmoidf_(float x) { return 1.f / (1.f + __expf(-x)); }
; DI void phaseF(int wv0, PP p, unsigned char* smem) {
;     ...
;             for (int j = 0; j < 4; ++j) acc[ai][0][m][n][j] *= sigmoidf_(acc[ai][1][m][n][j]);
;       __builtin_amdgcn_sched_barrier(0);
;       epi256(wv0, acc, brow, grp * 128, [&](int ai, int bj, int m, int n, int row, int col0, f32x4& v) {
;         if (bj == 0) {
;           const unsigned og = (unsigned)row * 2048u + 1024u + (unsigned)col0, om = (unsigned)row * 1024u + (unsigned)col0;
;           const uint2 gq = *(const uint2*)(MG + og);
;           *(uint2*)(MR + om) = pk4(__uint_as_float(gq.x << 16) * v[0], __uint_as_float(gq.x & 0xffff0000u) * v[1],
;                                    __uint_as_float(gq.y << 16) * v[2], __uint_as_float(gq.y & 0xffff0000u) * v[3]);
;         }
	v_lshlrev_b32_e32 v28, 16, v26
	v_and_b32_e32 v29, 0xffff0000, v26
	v_rcp_f32_e32 v26, v25
	s_nop 0
	v_fma_f32 v34, -v25, v26, 1.0
	v_fmac_f32_e32 v26, v34, v26
	v_div_scale_f32 v34, vcc, 1.0, v31, 1.0
	v_mul_f32_e32 v35, v34, v26
	v_fma_f32 v36, -v25, v35, v34
	v_fmac_f32_e32 v35, v36, v26
	v_fma_f32 v25, -v25, v35, v34
	v_div_fmas_f32 v25, v25, v26, v35
	v_div_fixup_f32 v31, v25, v31, 1.0
	v_div_scale_f32 v25, s[72:73], v30, v30, 1.0
	v_rcp_f32_e32 v26, v25
	s_nop 0
	v_fma_f32 v34, -v25, v26, 1.0
	v_fmac_f32_e32 v26, v34, v26
	v_div_scale_f32 v34, vcc, 1.0, v30, 1.0
	v_mul_f32_e32 v35, v34, v26
	v_fma_f32 v36, -v25, v35, v34
	v_fmac_f32_e32 v35, v36, v26
	v_fma_f32 v25, -v25, v35, v34
	v_div_fmas_f32 v25, v25, v26, v35
	v_div_fixup_f32 v30, v25, v30, 1.0
	v_pk_mul_f32 v[20:21], v[20:21], v[30:31]
	v_lshlrev_b32_e32 v26, 16, v27
	v_pk_mul_f32 v[20:21], v[20:21], v[28:29]
	v_pk_add_f32 v[28:29], v[92:93], 1.0 op_sel_hi:[1,0]
	v_and_b32_e32 v27, 0xffff0000, v27
	v_div_scale_f32 v25, s[72:73], v29, v29, 1.0
	v_rcp_f32_e32 v30, v25
	v_cvt_pk_bf16_f32 v20, v20, v21
	v_fma_f32 v31, -v25, v30, 1.0
	v_fmac_f32_e32 v30, v31, v30
	v_div_scale_f32 v31, vcc, 1.0, v29, 1.0
	v_mul_f32_e32 v34, v31, v30
	v_fma_f32 v35, -v25, v34, v31
	v_fmac_f32_e32 v34, v35, v30
	v_fma_f32 v25, -v25, v34, v31
	v_div_fmas_f32 v25, v25, v30, v34
	v_div_fixup_f32 v29, v25, v29, 1.0
	v_div_scale_f32 v25, s[72:73], v28, v28, 1.0
	v_rcp_f32_e32 v30, v25
	s_nop 0
	v_fma_f32 v31, -v25, v30, 1.0
	v_fmac_f32_e32 v30, v31, v30
	v_div_scale_f32 v31, vcc, 1.0, v28, 1.0
	v_mul_f32_e32 v34, v31, v30
	v_fma_f32 v35, -v25, v34, v31
	v_fmac_f32_e32 v34, v35, v30
	v_fma_f32 v25, -v25, v34, v31
	v_div_fmas_f32 v25, v25, v30, v34
	v_div_fixup_f32 v28, v25, v28, 1.0
	v_pk_mul_f32 v[22:23], v[22:23], v[28:29]
	v_mov_b32_e32 v25, v129
	v_pk_mul_f32 v[22:23], v[22:23], v[26:27]
	v_pk_add_f32 v[26:27], v[86:87], 1.0 op_sel_hi:[1,0]
	v_cvt_pk_bf16_f32 v21, v22, v23
	v_lshl_add_u64 v[22:23], v[24:25], 1, s[14:15]
	global_store_dwordx2 v[22:23], v[20:21], off
	v_lshl_add_u64 v[22:23], v[128:129], 1, s[12:13]
	global_load_dwordx2 v[22:23], v[22:23], off
	v_div_scale_f32 v21, s[72:73], v27, v27, 1.0
	v_add_u32_e32 v20, v62, v33
	s_waitcnt vmcnt(0)
	v_lshlrev_b32_e32 v24, 16, v22
	v_and_b32_e32 v25, 0xffff0000, v22
	v_rcp_f32_e32 v22, v21
	s_nop 0
	v_fma_f32 v28, -v21, v22, 1.0
	v_fmac_f32_e32 v22, v28, v22
	v_div_scale_f32 v28, vcc, 1.0, v27, 1.0
	v_mul_f32_e32 v29, v28, v22
	v_fma_f32 v30, -v21, v29, v28
	v_fmac_f32_e32 v29, v30, v22
	v_fma_f32 v21, -v21, v29, v28
	v_div_fmas_f32 v21, v21, v22, v29
	v_div_fixup_f32 v27, v21, v27, 1.0
	v_div_scale_f32 v21, s[72:73], v26, v26, 1.0
	v_rcp_f32_e32 v22, v21
	s_nop 0
	v_fma_f32 v28, -v21, v22, 1.0
	v_fmac_f32_e32 v22, v28, v22
	v_div_scale_f32 v28, vcc, 1.0, v26, 1.0
	v_mul_f32_e32 v29, v28, v22
	v_fma_f32 v30, -v21, v29, v28
	v_fmac_f32_e32 v29, v30, v22
	v_fma_f32 v21, -v21, v29, v28
	v_div_fmas_f32 v21, v21, v22, v29
	v_div_fixup_f32 v26, v21, v26, 1.0
	v_pk_mul_f32 v[16:17], v[16:17], v[26:27]
	v_lshlrev_b32_e32 v22, 16, v23
	v_pk_mul_f32 v[16:17], v[16:17], v[24:25]
	v_pk_add_f32 v[24:25], v[84:85], 1.0 op_sel_hi:[1,0]
	v_and_b32_e32 v23, 0xffff0000, v23
	v_div_scale_f32 v21, s[72:73], v25, v25, 1.0
	v_rcp_f32_e32 v26, v21
	v_cvt_pk_bf16_f32 v16, v16, v17
	v_fma_f32 v27, -v21, v26, 1.0
	v_fmac_f32_e32 v26, v27, v26
	v_div_scale_f32 v27, vcc, 1.0, v25, 1.0
	v_mul_f32_e32 v28, v27, v26
	v_fma_f32 v29, -v21, v28, v27
	v_fmac_f32_e32 v28, v29, v26
	v_fma_f32 v21, -v21, v28, v27
	v_div_fmas_f32 v21, v21, v26, v28
	v_div_fixup_f32 v25, v21, v25, 1.0
	v_div_scale_f32 v21, s[72:73], v24, v24, 1.0
	v_rcp_f32_e32 v26, v21
	s_nop 0
	v_fma_f32 v27, -v21, v26, 1.0
	v_fmac_f32_e32 v26, v27, v26
	v_div_scale_f32 v27, vcc, 1.0, v24, 1.0
	v_mul_f32_e32 v28, v27, v26
	v_fma_f32 v29, -v21, v28, v27
	v_fmac_f32_e32 v28, v29, v26
	v_fma_f32 v21, -v21, v28, v27
	v_div_fmas_f32 v21, v21, v26, v28
	v_div_fixup_f32 v24, v21, v24, 1.0
	v_pk_mul_f32 v[18:19], v[18:19], v[24:25]
	v_mov_b32_e32 v21, v129
	v_pk_mul_f32 v[18:19], v[18:19], v[22:23]
	s_nop 0
	v_cvt_pk_bf16_f32 v17, v18, v19
	v_lshl_add_u64 v[18:19], v[20:21], 1, s[14:15]
	global_store_dwordx2 v[18:19], v[16:17], off
	v_add_u32_e32 v16, 0xa0, v83
	v_lshl_or_b32 v24, v16, 11, v151
	v_or_b32_e32 v128, v24, v82
	v_lshl_add_u64 v[18:19], v[128:129], 1, s[12:13]
	global_load_dwordx2 v[18:19], v[18:19], off
	v_pk_add_f32 v[22:23], v[80:81], 1.0 op_sel_hi:[1,0]
	v_lshlrev_b32_e32 v25, 10, v16
	v_div_scale_f32 v17, s[72:73], v23, v23, 1.0
	v_or_b32_e32 v16, v25, v82
	v_add_u32_e32 v128, v24, v62
	s_waitcnt vmcnt(0)
; DI uint2 pk4(float a, float b, float c, float d) { uint2 o; o.x = pk2(a, b); o.y = pk2(c, d); return o; }
; DI float sigmoidf_(float x) { return 1.f / (1.f + __expf(-x)); }
; DI void phaseF(int wv0, PP p, unsigned char* smem) {
;     ...
;             for (int j = 0; j < 4; ++j) acc[ai][0][m][n][j] *= sigmoidf_(acc[ai][1][m][n][j]);
;       __builtin_amdgcn_sched_barrier(0);
;       epi256(wv0, acc, brow, grp * 128, [&](int ai, int bj, int m, int n, int row, int col0, f32x4& v) {
;         if (bj == 0) {
;           const unsigned og = (unsigned)row * 2048u + 1024u + (unsigned)col0, om = (unsigned)row * 1024u + (unsigned)col0;
;           const uint2 gq = *(const uint2*)(MG + og);
;           *(uint2*)(MR + om) = pk4(__uint_as_float(gq.x << 16) * v[0], __uint_as_float(gq.x & 0xffff0000u) * v[1],
;                                    __uint_as_float(gq.y << 16) * v[2], __uint_as_float(gq.y & 0xffff0000u) * v[3]);
;         }
	v_lshlrev_b32_e32 v20, 16, v18
	v_and_b32_e32 v21, 0xffff0000, v18
	v_rcp_f32_e32 v18, v17
	s_nop 0
	v_fma_f32 v26, -v17, v18, 1.0
	v_fmac_f32_e32 v18, v26, v18
	v_div_scale_f32 v26, vcc, 1.0, v23, 1.0
	v_mul_f32_e32 v27, v26, v18
	v_fma_f32 v28, -v17, v27, v26
	v_fmac_f32_e32 v27, v28, v18
	v_fma_f32 v17, -v17, v27, v26
	v_div_fmas_f32 v17, v17, v18, v27
	v_div_fixup_f32 v23, v17, v23, 1.0
	v_div_scale_f32 v17, s[72:73], v22, v22, 1.0
	v_rcp_f32_e32 v18, v17
	s_nop 0
	v_fma_f32 v26, -v17, v18, 1.0
	v_fmac_f32_e32 v18, v26, v18
	v_div_scale_f32 v26, vcc, 1.0, v22, 1.0
	v_mul_f32_e32 v27, v26, v18
	v_fma_f32 v28, -v17, v27, v26
	v_fmac_f32_e32 v27, v28, v18
	v_fma_f32 v17, -v17, v27, v26
	v_div_fmas_f32 v17, v17, v18, v27
	v_div_fixup_f32 v22, v17, v22, 1.0
	v_pk_mul_f32 v[12:13], v[12:13], v[22:23]
	v_lshlrev_b32_e32 v18, 16, v19
	v_pk_mul_f32 v[12:13], v[12:13], v[20:21]
	v_pk_add_f32 v[20:21], v[78:79], 1.0 op_sel_hi:[1,0]
	v_and_b32_e32 v19, 0xffff0000, v19
	v_div_scale_f32 v17, s[72:73], v21, v21, 1.0
	v_rcp_f32_e32 v22, v17
	v_cvt_pk_bf16_f32 v12, v12, v13
	v_fma_f32 v23, -v17, v22, 1.0
	v_fmac_f32_e32 v22, v23, v22
	v_div_scale_f32 v23, vcc, 1.0, v21, 1.0
	v_mul_f32_e32 v26, v23, v22
	v_fma_f32 v27, -v17, v26, v23
	v_fmac_f32_e32 v26, v27, v22
	v_fma_f32 v17, -v17, v26, v23
	v_div_fmas_f32 v17, v17, v22, v26
	v_div_fixup_f32 v21, v17, v21, 1.0
	v_div_scale_f32 v17, s[72:73], v20, v20, 1.0
	v_rcp_f32_e32 v22, v17
	s_nop 0
	v_fma_f32 v23, -v17, v22, 1.0
	v_fmac_f32_e32 v22, v23, v22
	v_div_scale_f32 v23, vcc, 1.0, v20, 1.0
	v_mul_f32_e32 v26, v23, v22
	v_fma_f32 v27, -v17, v26, v23
	v_fmac_f32_e32 v26, v27, v22
	v_fma_f32 v17, -v17, v26, v23
	v_div_fmas_f32 v17, v17, v22, v26
	v_div_fixup_f32 v20, v17, v20, 1.0
	v_pk_mul_f32 v[14:15], v[14:15], v[20:21]
	v_mov_b32_e32 v17, v129
	v_pk_mul_f32 v[14:15], v[14:15], v[18:19]
	v_pk_add_f32 v[18:19], v[76:77], 1.0 op_sel_hi:[1,0]
	v_cvt_pk_bf16_f32 v13, v14, v15
	v_lshl_add_u64 v[14:15], v[16:17], 1, s[14:15]
	global_store_dwordx2 v[14:15], v[12:13], off
	v_lshl_add_u64 v[14:15], v[128:129], 1, s[12:13]
	global_load_dwordx2 v[14:15], v[14:15], off
	v_div_scale_f32 v13, s[72:73], v19, v19, 1.0
	v_add_u32_e32 v12, v62, v25
	s_waitcnt vmcnt(0)
	v_lshlrev_b32_e32 v16, 16, v14
	v_and_b32_e32 v17, 0xffff0000, v14
	v_rcp_f32_e32 v14, v13
	s_nop 0
	v_fma_f32 v20, -v13, v14, 1.0
	v_fmac_f32_e32 v14, v20, v14
	v_div_scale_f32 v20, vcc, 1.0, v19, 1.0
	v_mul_f32_e32 v21, v20, v14
	v_fma_f32 v22, -v13, v21, v20
	v_fmac_f32_e32 v21, v22, v14
	v_fma_f32 v13, -v13, v21, v20
	v_div_fmas_f32 v13, v13, v14, v21
	v_div_fixup_f32 v19, v13, v19, 1.0
	v_div_scale_f32 v13, s[72:73], v18, v18, 1.0
	v_rcp_f32_e32 v14, v13
	s_nop 0
	v_fma_f32 v20, -v13, v14, 1.0
	v_fmac_f32_e32 v14, v20, v14
	v_div_scale_f32 v20, vcc, 1.0, v18, 1.0
	v_mul_f32_e32 v21, v20, v14
	v_fma_f32 v22, -v13, v21, v20
	v_fmac_f32_e32 v21, v22, v14
	v_fma_f32 v13, -v13, v21, v20
	v_div_fmas_f32 v13, v13, v14, v21
	v_div_fixup_f32 v18, v13, v18, 1.0
	v_pk_mul_f32 v[8:9], v[8:9], v[18:19]
	v_lshlrev_b32_e32 v14, 16, v15
	v_pk_mul_f32 v[8:9], v[8:9], v[16:17]
	v_pk_add_f32 v[16:17], v[74:75], 1.0 op_sel_hi:[1,0]
	v_and_b32_e32 v15, 0xffff0000, v15
	v_div_scale_f32 v13, s[72:73], v17, v17, 1.0
	v_rcp_f32_e32 v18, v13
	v_cvt_pk_bf16_f32 v8, v8, v9
	v_fma_f32 v19, -v13, v18, 1.0
	v_fmac_f32_e32 v18, v19, v18
	v_div_scale_f32 v19, vcc, 1.0, v17, 1.0
	v_mul_f32_e32 v20, v19, v18
	v_fma_f32 v21, -v13, v20, v19
	v_fmac_f32_e32 v20, v21, v18
	v_fma_f32 v13, -v13, v20, v19
	v_div_fmas_f32 v13, v13, v18, v20
	v_div_fixup_f32 v17, v13, v17, 1.0
	v_div_scale_f32 v13, s[72:73], v16, v16, 1.0
	v_rcp_f32_e32 v18, v13
	s_nop 0
	v_fma_f32 v19, -v13, v18, 1.0
	v_fmac_f32_e32 v18, v19, v18
	v_div_scale_f32 v19, vcc, 1.0, v16, 1.0
	v_mul_f32_e32 v20, v19, v18
	v_fma_f32 v21, -v13, v20, v19
	v_fmac_f32_e32 v20, v21, v18
	v_fma_f32 v13, -v13, v20, v19
	v_div_fmas_f32 v13, v13, v18, v20
	v_div_fixup_f32 v16, v13, v16, 1.0
	v_pk_mul_f32 v[10:11], v[10:11], v[16:17]
	v_mov_b32_e32 v13, v129
	v_pk_mul_f32 v[10:11], v[10:11], v[14:15]
	v_pk_add_f32 v[14:15], v[72:73], 1.0 op_sel_hi:[1,0]
	v_cvt_pk_bf16_f32 v9, v10, v11
	v_lshl_add_u64 v[10:11], v[12:13], 1, s[14:15]
	global_store_dwordx2 v[10:11], v[8:9], off
	v_add_u32_e32 v8, 0xb0, v83
	v_lshl_or_b32 v16, v8, 11, v151
	v_or_b32_e32 v128, v16, v82
	v_lshl_add_u64 v[10:11], v[128:129], 1, s[12:13]
	global_load_dwordx2 v[10:11], v[10:11], off
	v_div_scale_f32 v9, s[72:73], v15, v15, 1.0
	v_lshlrev_b32_e32 v17, 10, v8
	v_or_b32_e32 v8, v17, v82
	v_add_u32_e32 v128, v16, v62
	s_waitcnt vmcnt(0)
; DI uint2 pk4(float a, float b, float c, float d) { uint2 o; o.x = pk2(a, b); o.y = pk2(c, d); return o; }
; DI float sigmoidf_(float x) { return 1.f / (1.f + __expf(-x)); }
; DI void phaseF(int wv0, PP p, unsigned char* smem) {
;     ...
;             for (int j = 0; j < 4; ++j) acc[ai][0][m][n][j] *= sigmoidf_(acc[ai][1][m][n][j]);
;       __builtin_amdgcn_sched_barrier(0);
;       epi256(wv0, acc, brow, grp * 128, [&](int ai, int bj, int m, int n, int row, int col0, f32x4& v) {
;         if (bj == 0) {
;           const unsigned og = (unsigned)row * 2048u + 1024u + (unsigned)col0, om = (unsigned)row * 1024u + (unsigned)col0;
;           const uint2 gq = *(const uint2*)(MG + og);
;           *(uint2*)(MR + om) = pk4(__uint_as_float(gq.x << 16) * v[0], __uint_as_float(gq.x & 0xffff0000u) * v[1],
;                                    __uint_as_float(gq.y << 16) * v[2], __uint_as_float(gq.y & 0xffff0000u) * v[3]);
;         }
;       });
	v_lshlrev_b32_e32 v12, 16, v10
	v_and_b32_e32 v13, 0xffff0000, v10
	v_rcp_f32_e32 v10, v9
	s_nop 0
	v_fma_f32 v18, -v9, v10, 1.0
	v_fmac_f32_e32 v10, v18, v10
	v_div_scale_f32 v18, vcc, 1.0, v15, 1.0
	v_mul_f32_e32 v19, v18, v10
	v_fma_f32 v20, -v9, v19, v18
	v_fmac_f32_e32 v19, v20, v10
	v_fma_f32 v9, -v9, v19, v18
	v_div_fmas_f32 v9, v9, v10, v19
	v_div_fixup_f32 v15, v9, v15, 1.0
	v_div_scale_f32 v9, s[72:73], v14, v14, 1.0
	v_rcp_f32_e32 v10, v9
	s_nop 0
	v_fma_f32 v18, -v9, v10, 1.0
	v_fmac_f32_e32 v10, v18, v10
	v_div_scale_f32 v18, vcc, 1.0, v14, 1.0
	v_mul_f32_e32 v19, v18, v10
	v_fma_f32 v20, -v9, v19, v18
	v_fmac_f32_e32 v19, v20, v10
	v_fma_f32 v9, -v9, v19, v18
	v_div_fmas_f32 v9, v9, v10, v19
	v_div_fixup_f32 v14, v9, v14, 1.0
	v_pk_mul_f32 v[4:5], v[4:5], v[14:15]
	v_lshlrev_b32_e32 v10, 16, v11
	v_pk_mul_f32 v[4:5], v[4:5], v[12:13]
	v_pk_add_f32 v[12:13], v[70:71], 1.0 op_sel_hi:[1,0]
	v_and_b32_e32 v11, 0xffff0000, v11
	v_div_scale_f32 v9, s[72:73], v13, v13, 1.0
	v_rcp_f32_e32 v14, v9
	v_cvt_pk_bf16_f32 v4, v4, v5
	v_fma_f32 v15, -v9, v14, 1.0
	v_fmac_f32_e32 v14, v15, v14
	v_div_scale_f32 v15, vcc, 1.0, v13, 1.0
	v_mul_f32_e32 v18, v15, v14
	v_fma_f32 v19, -v9, v18, v15
	v_fmac_f32_e32 v18, v19, v14
	v_fma_f32 v9, -v9, v18, v15
	v_div_fmas_f32 v9, v9, v14, v18
	v_div_fixup_f32 v13, v9, v13, 1.0
	v_div_scale_f32 v9, s[72:73], v12, v12, 1.0
	v_rcp_f32_e32 v14, v9
	s_nop 0
	v_fma_f32 v15, -v9, v14, 1.0
	v_fmac_f32_e32 v14, v15, v14
	v_div_scale_f32 v15, vcc, 1.0, v12, 1.0
	v_mul_f32_e32 v18, v15, v14
	v_fma_f32 v19, -v9, v18, v15
	v_fmac_f32_e32 v18, v19, v14
	v_fma_f32 v9, -v9, v18, v15
	v_div_fmas_f32 v9, v9, v14, v18
	v_div_fixup_f32 v12, v9, v12, 1.0
	v_pk_mul_f32 v[6:7], v[6:7], v[12:13]
	v_mov_b32_e32 v9, v129
	v_pk_mul_f32 v[6:7], v[6:7], v[10:11]
	v_pk_add_f32 v[10:11], v[68:69], 1.0 op_sel_hi:[1,0]
	v_cvt_pk_bf16_f32 v5, v6, v7
	v_lshl_add_u64 v[6:7], v[8:9], 1, s[14:15]
	global_store_dwordx2 v[6:7], v[4:5], off
	v_lshl_add_u64 v[6:7], v[128:129], 1, s[12:13]
	global_load_dwordx2 v[6:7], v[6:7], off
	v_div_scale_f32 v5, s[72:73], v11, v11, 1.0
	v_add_u32_e32 v4, v62, v17
	s_waitcnt vmcnt(0)
	v_lshlrev_b32_e32 v8, 16, v6
	v_and_b32_e32 v9, 0xffff0000, v6
	v_rcp_f32_e32 v6, v5
	s_nop 0
	v_fma_f32 v12, -v5, v6, 1.0
	v_fmac_f32_e32 v6, v12, v6
	v_div_scale_f32 v12, vcc, 1.0, v11, 1.0
	v_mul_f32_e32 v13, v12, v6
	v_fma_f32 v14, -v5, v13, v12
	v_fmac_f32_e32 v13, v14, v6
	v_fma_f32 v5, -v5, v13, v12
	v_div_fmas_f32 v5, v5, v6, v13
	v_div_fixup_f32 v11, v5, v11, 1.0
	v_div_scale_f32 v5, s[72:73], v10, v10, 1.0
	v_rcp_f32_e32 v6, v5
	s_nop 0
	v_fma_f32 v12, -v5, v6, 1.0
	v_fmac_f32_e32 v6, v12, v6
	v_div_scale_f32 v12, vcc, 1.0, v10, 1.0
	v_mul_f32_e32 v13, v12, v6
	v_fma_f32 v14, -v5, v13, v12
	v_fmac_f32_e32 v13, v14, v6
	v_fma_f32 v5, -v5, v13, v12
	v_div_fmas_f32 v5, v5, v6, v13
	v_div_fixup_f32 v10, v5, v10, 1.0
	v_pk_mul_f32 v[0:1], v[0:1], v[10:11]
	v_lshlrev_b32_e32 v6, 16, v7
	v_pk_mul_f32 v[0:1], v[0:1], v[8:9]
	v_pk_add_f32 v[8:9], v[64:65], 1.0 op_sel_hi:[1,0]
	v_and_b32_e32 v7, 0xffff0000, v7
	v_div_scale_f32 v5, s[72:73], v9, v9, 1.0
	v_rcp_f32_e32 v10, v5
	v_cvt_pk_bf16_f32 v0, v0, v1
	v_fma_f32 v11, -v5, v10, 1.0
	v_fmac_f32_e32 v10, v11, v10
	v_div_scale_f32 v11, vcc, 1.0, v9, 1.0
	v_mul_f32_e32 v12, v11, v10
	v_fma_f32 v13, -v5, v12, v11
	v_fmac_f32_e32 v12, v13, v10
	v_fma_f32 v5, -v5, v12, v11
	v_div_fmas_f32 v5, v5, v10, v12
	v_div_fixup_f32 v9, v5, v9, 1.0
	v_div_scale_f32 v5, s[72:73], v8, v8, 1.0
	v_rcp_f32_e32 v10, v5
	s_nop 0
	v_fma_f32 v11, -v5, v10, 1.0
	v_fmac_f32_e32 v10, v11, v10
	v_div_scale_f32 v11, vcc, 1.0, v8, 1.0
	v_mul_f32_e32 v12, v11, v10
	v_fma_f32 v13, -v5, v12, v11
	v_fmac_f32_e32 v12, v13, v10
	v_fma_f32 v5, -v5, v12, v11
	v_div_fmas_f32 v5, v5, v10, v12
	v_div_fixup_f32 v8, v5, v8, 1.0
	v_pk_mul_f32 v[2:3], v[2:3], v[8:9]
	v_mov_b32_e32 v5, v129
	v_pk_mul_f32 v[2:3], v[2:3], v[6:7]
	s_nop 0
	v_cvt_pk_bf16_f32 v1, v2, v3
	v_lshl_add_u64 v[2:3], v[4:5], 1, s[14:15]
	global_store_dwordx2 v[2:3], v[0:1], off
	s_mov_b64 s[72:73], 0
	s_and_b64 vcc, exec, s[70:71]
	s_cbranch_vccnz .LBB0_989
